# phase 5 tail tiles placed one per CU on all XCDs (physical workgroups 0..127) instead of two per CU on XCDs 0 and 1
# speedup vs baseline: 1.0017x; 1.0017x over previous
; DI float4 ntld4(const float* p) { const f32x4 v = __builtin_nontemporal_load((const f32x4*)p); return (float4){v[0], v[1], v[2], v[3]}; }
; DI void gemm_out(const Params& p, char* lds) {
;     ...
;         float4 xres[3][4];
; #pragma unroll
;         for (int tt = 0; tt < 3; ++tt) { const int row = m0 + wm * 48 + tt * 16 + q; const float* xr = row < NTP ? p.x_p + (size_t)row * DM : p.x_s + (size_t)(row - NTP) * DM;
; #pragma unroll
;             for (int ct = 0; ct < 4; ++ct) xres[tt][ct] = ntld4(xr + n0 + wn * 64 + ct * 16 + 4 * g); }
;     ...
;         for (int kt = 0; kt < 16; ++kt) {
;             if (kt + 1 < 16) OSTAGE((kt + 1) & 1, kt + 1);
;             const char* sb = lds + (kt & 1) * 28672; const char* sa = sb + 16384;
; #pragma unroll
;             for (int ks = 0; ks < 2; ++ks) {
;                 bf16x8 fw[4], fx[3];
; #pragma unroll
;                 for (int ct = 0; ct < 4; ++ct) fw[ct] = *(const bf16x8*)(sb + swz(wn * 64 + ct * 16 + q, 4 * ks + g));
; #pragma unroll
;                 for (int tt = 0; tt < 3; ++tt) fx[tt] = *(const bf16x8*)(sa + swz(wm * 48 + tt * 16 + q, 4 * ks + g));
; #pragma unroll
;                 for (int ct = 0; ct < 4; ++ct)
; #pragma unroll
;                     for (int tt = 0; tt < 3; ++tt) acc[ct][tt] = __builtin_amdgcn_mfma_f32_16x16x32_bf16(fw[ct], fx[tt], acc[ct][tt], 0, 0, 0);
;             }
;             __syncthreads();
;         }
.Lo_skipnext:
	v_readfirstlane_b32 s96, v0
	s_lshr_b32 s96, s96, 6
	s_lshr_b32 s98, s96, 1
	s_and_b32 s96, s96, 1
	s_lshl_b32 s97, s96, 6
	s_add_i32 s97, s97, s82
	s_cmp_lt_u32 s82, 0x4000
	s_cselect_b32 s2, s56, s58
	s_cselect_b32 s3, s57, s59
	s_cselect_b32 s99, 0, 0x4000
	s_sub_i32 s99, s97, s99
	s_lshl_b32 s98, s98, 6
	s_add_i32 s98, s98, s0
	v_and_b32_e32 v184, 31, v0
	v_bfe_u32 v185, v0, 5, 1
	v_lshlrev_b32_e32 v185, 14, v185
	v_add_u32_e32 v186, s98, v184
	v_lshl_add_u32 v186, v186, 2, v185
	s_lshl_b32 s97, s97, 12
	s_lshl_b32 s99, s99, 12
	v_add_u32_e32 v188, s97, v186
	v_add_u32_e32 v187, s99, v186
	v_mfma_f32_32x32x16_bf16 v[34:49], v[80:83], v[76:79], v[34:49]
	global_load_dword v120, v187, s[2:3] nt
	global_load_dword v121, v187, s[2:3] offset:128 nt
	v_add_u32_e32 v187, 0x1000, v187
	global_load_dword v122, v187, s[2:3] nt
	global_load_dword v123, v187, s[2:3] offset:128 nt
	v_add_u32_e32 v187, 0x1000, v187
	v_mfma_f32_32x32x16_bf16 v[18:33], v[84:87], v[76:79], v[18:33]
	global_load_dword v124, v187, s[2:3] nt
	global_load_dword v125, v187, s[2:3] offset:128 nt
	v_add_u32_e32 v187, 0x1000, v187
	global_load_dword v126, v187, s[2:3] nt
	global_load_dword v127, v187, s[2:3] offset:128 nt
	v_add_u32_e32 v187, 0x5000, v187
	v_mfma_f32_32x32x16_bf16 v[50:65], v[80:83], v[88:91], v[50:65]
	global_load_dword v128, v187, s[2:3] nt
	global_load_dword v129, v187, s[2:3] offset:128 nt
	v_add_u32_e32 v187, 0x1000, v187
	global_load_dword v130, v187, s[2:3] nt
	global_load_dword v131, v187, s[2:3] offset:128 nt
	v_add_u32_e32 v187, 0x1000, v187
	v_mfma_f32_32x32x16_bf16 v[2:17], v[84:87], v[88:91], v[2:17]
	global_load_dword v132, v187, s[2:3] nt
	global_load_dword v133, v187, s[2:3] offset:128 nt
	v_add_u32_e32 v187, 0x1000, v187
	global_load_dword v134, v187, s[2:3] nt
	global_load_dword v135, v187, s[2:3] offset:128 nt
	v_add_u32_e32 v187, 0x5000, v187
	ds_read_b128 v[76:79], v96 offset:32768
	ds_read_b128 v[80:83], v96 offset:36864
	ds_read_b128 v[84:87], v74 offset:49152
	ds_read_b128 v[88:91], v74 offset:53248
	s_waitcnt lgkmcnt(1)
	v_mfma_f32_32x32x16_bf16 v[34:49], v[76:79], v[84:87], v[34:49]
	global_load_dword v136, v187, s[2:3] nt
	global_load_dword v137, v187, s[2:3] offset:128 nt
	v_add_u32_e32 v187, 0x1000, v187
	global_load_dword v138, v187, s[2:3] nt
	global_load_dword v139, v187, s[2:3] offset:128 nt
	v_add_u32_e32 v187, 0x1000, v187
	v_mfma_f32_32x32x16_bf16 v[18:33], v[80:83], v[84:87], v[18:33]
	global_load_dword v140, v187, s[2:3] nt
	global_load_dword v141, v187, s[2:3] offset:128 nt
	v_add_u32_e32 v187, 0x1000, v187
	global_load_dword v142, v187, s[2:3] nt
	global_load_dword v143, v187, s[2:3] offset:128 nt
	v_add_u32_e32 v187, 0x5000, v187
	s_waitcnt lgkmcnt(0)
	v_mfma_f32_32x32x16_bf16 v[50:65], v[76:79], v[88:91], v[50:65]
	global_load_dword v144, v187, s[2:3] nt
	global_load_dword v145, v187, s[2:3] offset:128 nt
	v_add_u32_e32 v187, 0x1000, v187
	global_load_dword v146, v187, s[2:3] nt
	global_load_dword v147, v187, s[2:3] offset:128 nt
	v_add_u32_e32 v187, 0x1000, v187
	v_mfma_f32_32x32x16_bf16 v[2:17], v[80:83], v[88:91], v[2:17]
	global_load_dword v148, v187, s[2:3] nt
	global_load_dword v149, v187, s[2:3] offset:128 nt
	v_add_u32_e32 v187, 0x1000, v187
	global_load_dword v150, v187, s[2:3] nt
	global_load_dword v151, v187, s[2:3] offset:128 nt
	v_add_u32_e32 v187, 0x5000, v187
	ds_read_b128 v[76:79], v95 offset:49152
	ds_read_b128 v[80:83], v97 offset:32768
	ds_read_b128 v[84:87], v97 offset:36864
	ds_read_b128 v[88:91], v95 offset:53248
	s_waitcnt lgkmcnt(2)
	v_mfma_f32_32x32x16_bf16 v[34:49], v[80:83], v[76:79], v[34:49]
	global_load_dword v152, v187, s[2:3] nt
	global_load_dword v153, v187, s[2:3] offset:128 nt
	v_add_u32_e32 v187, 0x1000, v187
	global_load_dword v154, v187, s[2:3] nt
	global_load_dword v155, v187, s[2:3] offset:128 nt
	v_add_u32_e32 v187, 0x1000, v187
	s_waitcnt lgkmcnt(1)
	v_mfma_f32_32x32x16_bf16 v[18:33], v[84:87], v[76:79], v[18:33]
	global_load_dword v156, v187, s[2:3] nt
	global_load_dword v157, v187, s[2:3] offset:128 nt
	v_add_u32_e32 v187, 0x1000, v187
	global_load_dword v158, v187, s[2:3] nt
	global_load_dword v159, v187, s[2:3] offset:128 nt
	v_add_u32_e32 v187, 0x5000, v187
	s_waitcnt lgkmcnt(0)
	v_mfma_f32_32x32x16_bf16 v[50:65], v[80:83], v[88:91], v[50:65]
	global_load_dword v160, v187, s[2:3] nt
	global_load_dword v161, v187, s[2:3] offset:128 nt
	v_add_u32_e32 v187, 0x1000, v187
	global_load_dword v162, v187, s[2:3] nt
	global_load_dword v163, v187, s[2:3] offset:128 nt
	v_add_u32_e32 v187, 0x1000, v187
	v_mfma_f32_32x32x16_bf16 v[2:17], v[84:87], v[88:91], v[2:17]
	global_load_dword v164, v187, s[2:3] nt
	global_load_dword v165, v187, s[2:3] offset:128 nt
	v_add_u32_e32 v187, 0x1000, v187
	global_load_dword v166, v187, s[2:3] nt
	global_load_dword v167, v187, s[2:3] offset:128 nt
	v_add_u32_e32 v187, 0x5000, v187
	ds_read_b128 v[76:79], v98 offset:49152
	ds_read_b128 v[80:83], v99 offset:32768
	ds_read_b128 v[84:87], v99 offset:36864
	ds_read_b128 v[88:91], v98 offset:53248
	s_waitcnt lgkmcnt(2)
	v_mfma_f32_32x32x16_bf16 v[34:49], v[80:83], v[76:79], v[34:49]
	global_load_dword v168, v187, s[2:3] nt
	global_load_dword v169, v187, s[2:3] offset:128 nt
	v_add_u32_e32 v187, 0x1000, v187
	global_load_dword v170, v187, s[2:3] nt
	global_load_dword v171, v187, s[2:3] offset:128 nt
	v_add_u32_e32 v187, 0x1000, v187
	s_waitcnt lgkmcnt(1)
	v_mfma_f32_32x32x16_bf16 v[18:33], v[84:87], v[76:79], v[18:33]
	global_load_dword v172, v187, s[2:3] nt
	global_load_dword v173, v187, s[2:3] offset:128 nt
	v_add_u32_e32 v187, 0x1000, v187
	global_load_dword v174, v187, s[2:3] nt
	global_load_dword v175, v187, s[2:3] offset:128 nt
	v_add_u32_e32 v187, 0x5000, v187
	s_waitcnt lgkmcnt(0)
	v_mfma_f32_32x32x16_bf16 v[50:65], v[80:83], v[88:91], v[50:65]
	global_load_dword v176, v187, s[2:3] nt
	global_load_dword v177, v187, s[2:3] offset:128 nt
	v_add_u32_e32 v187, 0x1000, v187
	global_load_dword v178, v187, s[2:3] nt
	global_load_dword v179, v187, s[2:3] offset:128 nt
	v_add_u32_e32 v187, 0x1000, v187
	v_mfma_f32_32x32x16_bf16 v[2:17], v[84:87], v[88:91], v[2:17]
	global_load_dword v180, v187, s[2:3] nt
	global_load_dword v181, v187, s[2:3] offset:128 nt
	v_add_u32_e32 v187, 0x1000, v187
	global_load_dword v182, v187, s[2:3] nt
	global_load_dword v183, v187, s[2:3] offset:128 nt
	ds_read_b128 v[76:79], v100 offset:49152
	ds_read_b128 v[80:83], v101 offset:32768
	ds_read_b128 v[84:87], v101 offset:36864
	ds_read_b128 v[88:91], v100 offset:53248
	s_waitcnt lgkmcnt(0)
	s_barrier
; DI void gemm_out(const Params& p, char* lds) {
;     ...
; #pragma unroll
;         for (int tt = 0; tt < 3; ++tt) {
;             const int row = m0 + wm * 48 + tt * 16 + q;
;             const float* xr = row < NTP ? p.x_p + (size_t)row * DM : p.x_s + (size_t)(row - NTP) * DM;
;             float* o = p.out + (size_t)row * DM;
; #pragma unroll
;             for (int ct = 0; ct < 4; ++ct) { const int col = n0 + wn * 64 + ct * 16 + 4 * g; const float4 xv = xres[tt][ct];
;                 const f32x4 w = {xv.x + acc[ct][tt][0], xv.y + acc[ct][tt][1], xv.z + acc[ct][tt][2], xv.w + acc[ct][tt][3]}; __builtin_nontemporal_store(w, (f32x4*)(o + col)); }
;         }
	v_mfma_f32_32x32x16_bf16 v[34:49], v[80:83], v[76:79], v[34:49]
	v_mfma_f32_32x32x16_bf16 v[18:33], v[84:87], v[76:79], v[18:33]
	v_mfma_f32_32x32x16_bf16 v[50:65], v[80:83], v[88:91], v[50:65]
	v_mfma_f32_32x32x16_bf16 v[2:17], v[84:87], v[88:91], v[2:17]
	s_nop 11
	s_waitcnt vmcnt(63)
	v_add_f32_e32 v34, v34, v120
	global_store_dword v188, v34, s[52:53] nt
	s_waitcnt vmcnt(63)
	v_add_f32_e32 v50, v50, v121
	global_store_dword v188, v50, s[52:53] offset:128 nt
	v_add_u32_e32 v188, 0x1000, v188
	s_waitcnt vmcnt(63)
	v_add_f32_e32 v35, v35, v122
	global_store_dword v188, v35, s[52:53] nt
	s_waitcnt vmcnt(63)
	v_add_f32_e32 v51, v51, v123
	global_store_dword v188, v51, s[52:53] offset:128 nt
	v_add_u32_e32 v188, 0x1000, v188
	s_waitcnt vmcnt(63)
	v_add_f32_e32 v36, v36, v124
	global_store_dword v188, v36, s[52:53] nt
	s_waitcnt vmcnt(63)
	v_add_f32_e32 v52, v52, v125
	global_store_dword v188, v52, s[52:53] offset:128 nt
	v_add_u32_e32 v188, 0x1000, v188
	s_waitcnt vmcnt(63)
	v_add_f32_e32 v37, v37, v126
	global_store_dword v188, v37, s[52:53] nt
	s_waitcnt vmcnt(63)
	v_add_f32_e32 v53, v53, v127
	global_store_dword v188, v53, s[52:53] offset:128 nt
	v_add_u32_e32 v188, 0x5000, v188
	s_waitcnt vmcnt(63)
	v_add_f32_e32 v38, v38, v128
	global_store_dword v188, v38, s[52:53] nt
	s_waitcnt vmcnt(63)
	v_add_f32_e32 v54, v54, v129
	global_store_dword v188, v54, s[52:53] offset:128 nt
	v_add_u32_e32 v188, 0x1000, v188
	s_waitcnt vmcnt(63)
	v_add_f32_e32 v39, v39, v130
	global_store_dword v188, v39, s[52:53] nt
	s_waitcnt vmcnt(63)
	v_add_f32_e32 v55, v55, v131
	global_store_dword v188, v55, s[52:53] offset:128 nt
	v_add_u32_e32 v188, 0x1000, v188
	s_waitcnt vmcnt(63)
	v_add_f32_e32 v40, v40, v132
	global_store_dword v188, v40, s[52:53] nt
	s_waitcnt vmcnt(63)
	v_add_f32_e32 v56, v56, v133
	global_store_dword v188, v56, s[52:53] offset:128 nt
	v_add_u32_e32 v188, 0x1000, v188
	s_waitcnt vmcnt(63)
	v_add_f32_e32 v41, v41, v134
	global_store_dword v188, v41, s[52:53] nt
	s_waitcnt vmcnt(63)
	v_add_f32_e32 v57, v57, v135
	global_store_dword v188, v57, s[52:53] offset:128 nt
	v_add_u32_e32 v188, 0x5000, v188
	s_waitcnt vmcnt(63)
	v_add_f32_e32 v42, v42, v136
	global_store_dword v188, v42, s[52:53] nt
	s_waitcnt vmcnt(63)
	v_add_f32_e32 v58, v58, v137
	global_store_dword v188, v58, s[52:53] offset:128 nt
	v_add_u32_e32 v188, 0x1000, v188
	s_waitcnt vmcnt(63)
	v_add_f32_e32 v43, v43, v138
	global_store_dword v188, v43, s[52:53] nt
	s_waitcnt vmcnt(63)
	v_add_f32_e32 v59, v59, v139
	global_store_dword v188, v59, s[52:53] offset:128 nt
	v_add_u32_e32 v188, 0x1000, v188
	s_waitcnt vmcnt(63)
	v_add_f32_e32 v44, v44, v140
	global_store_dword v188, v44, s[52:53] nt
	s_waitcnt vmcnt(63)
	v_add_f32_e32 v60, v60, v141
	global_store_dword v188, v60, s[52:53] offset:128 nt
	v_add_u32_e32 v188, 0x1000, v188
	s_waitcnt vmcnt(63)
	v_add_f32_e32 v45, v45, v142
	global_store_dword v188, v45, s[52:53] nt
	s_waitcnt vmcnt(63)
	v_add_f32_e32 v61, v61, v143
	global_store_dword v188, v61, s[52:53] offset:128 nt
	v_add_u32_e32 v188, 0x5000, v188
	s_waitcnt vmcnt(63)
	v_add_f32_e32 v46, v46, v144
	global_store_dword v188, v46, s[52:53] nt
	s_waitcnt vmcnt(63)
	v_add_f32_e32 v62, v62, v145
	global_store_dword v188, v62, s[52:53] offset:128 nt
	v_add_u32_e32 v188, 0x1000, v188
	s_waitcnt vmcnt(63)
	v_add_f32_e32 v47, v47, v146
	global_store_dword v188, v47, s[52:53] nt
	s_waitcnt vmcnt(63)
	v_add_f32_e32 v63, v63, v147
	global_store_dword v188, v63, s[52:53] offset:128 nt
	v_add_u32_e32 v188, 0x1000, v188
	s_waitcnt vmcnt(63)
	v_add_f32_e32 v48, v48, v148
	global_store_dword v188, v48, s[52:53] nt
	s_waitcnt vmcnt(63)
	v_add_f32_e32 v64, v64, v149
	global_store_dword v188, v64, s[52:53] offset:128 nt
	v_add_u32_e32 v188, 0x1000, v188
	s_waitcnt vmcnt(63)
	v_add_f32_e32 v49, v49, v150
	global_store_dword v188, v49, s[52:53] nt
	s_waitcnt vmcnt(63)
	v_add_f32_e32 v65, v65, v151
	global_store_dword v188, v65, s[52:53] offset:128 nt
	v_add_u32_e32 v188, 0x5000, v188
	s_waitcnt vmcnt(63)
	v_add_f32_e32 v18, v18, v152
	global_store_dword v188, v18, s[52:53] nt
	s_waitcnt vmcnt(63)
	v_add_f32_e32 v2, v2, v153
	global_store_dword v188, v2, s[52:53] offset:128 nt
	v_add_u32_e32 v188, 0x1000, v188
	s_waitcnt vmcnt(63)
	v_add_f32_e32 v19, v19, v154
	global_store_dword v188, v19, s[52:53] nt
	s_waitcnt vmcnt(63)
	v_add_f32_e32 v3, v3, v155
	global_store_dword v188, v3, s[52:53] offset:128 nt
	v_add_u32_e32 v188, 0x1000, v188
	s_waitcnt vmcnt(63)
	v_add_f32_e32 v20, v20, v156
	global_store_dword v188, v20, s[52:53] nt
	s_waitcnt vmcnt(63)
	v_add_f32_e32 v4, v4, v157
	global_store_dword v188, v4, s[52:53] offset:128 nt
	v_add_u32_e32 v188, 0x1000, v188
	s_waitcnt vmcnt(63)
	v_add_f32_e32 v21, v21, v158
	global_store_dword v188, v21, s[52:53] nt
	s_waitcnt vmcnt(63)
	v_add_f32_e32 v5, v5, v159
	global_store_dword v188, v5, s[52:53] offset:128 nt
	v_add_u32_e32 v188, 0x5000, v188
	s_waitcnt vmcnt(63)
	v_add_f32_e32 v22, v22, v160
	global_store_dword v188, v22, s[52:53] nt
	s_waitcnt vmcnt(63)
	v_add_f32_e32 v6, v6, v161
	global_store_dword v188, v6, s[52:53] offset:128 nt
	v_add_u32_e32 v188, 0x1000, v188
	s_waitcnt vmcnt(63)
	v_add_f32_e32 v23, v23, v162
	global_store_dword v188, v23, s[52:53] nt
	s_waitcnt vmcnt(63)
	v_add_f32_e32 v7, v7, v163
	global_store_dword v188, v7, s[52:53] offset:128 nt
	v_add_u32_e32 v188, 0x1000, v188
	s_waitcnt vmcnt(63)
	v_add_f32_e32 v24, v24, v164
	global_store_dword v188, v24, s[52:53] nt
	s_waitcnt vmcnt(63)
	v_add_f32_e32 v8, v8, v165
	global_store_dword v188, v8, s[52:53] offset:128 nt
	v_add_u32_e32 v188, 0x1000, v188
	s_waitcnt vmcnt(63)
; DI float4 ntld4(const float* p) { const f32x4 v = __builtin_nontemporal_load((const f32x4*)p); return (float4){v[0], v[1], v[2], v[3]}; }
; DI void gemm_out(const Params& p, char* lds) {
;     ...
;     for (int tile = vb; tile < ntile; tile += gridDim.x) {
;         int tid = threadIdx.x; asm volatile("" : "+v"(tid));
;         const int lane = tid & 63, wave = __builtin_amdgcn_readfirstlane(tid >> 6); const int wn = wave >> 1, wm = wave & 1; const int q = lane & 15, g = lane >> 4;
;         const int mt = tile >> 3, nt = tile & 7; const int m0 = mt * 96, n0 = nt * 128;
;         f32x4 acc[4][3];
; #pragma unroll
;         for (int a = 0; a < 4; ++a)
; #pragma unroll
;             for (int b = 0; b < 3; ++b) acc[a][b] = (f32x4){0.f, 0.f, 0.f, 0.f};
;         unsigned soffb[4], soffa[3];
; #pragma unroll
;         for (int i = 0; i < 4; ++i) { const int row = 8 * (i * 4 + wave) + (lane >> 3); const int ch = (lane & 7) ^ ((row >> 1) & 7); soffb[i] = (unsigned)(row * 1024 + ch * 8); }
; #pragma unroll
;         for (int i = 0; i < 3; ++i) { const int row = 8 * (i * 4 + wave) + (lane >> 3); const int ch = (lane & 7) ^ ((row >> 1) & 7); soffa[i] = (unsigned)(row * 1024 + ch * 8); }
;         const u16* ga = A + (size_t)m0 * 1024; const u16* gb = B + (size_t)n0 * 1024;
;     ...
;         OSTAGE(0, 0);
;         float4 xres[3][4];
; #pragma unroll
;         for (int tt = 0; tt < 3; ++tt) { const int row = m0 + wm * 48 + tt * 16 + q; const float* xr = row < NTP ? p.x_p + (size_t)row * DM : p.x_s + (size_t)(row - NTP) * DM;
; #pragma unroll
;             for (int ct = 0; ct < 4; ++ct) xres[tt][ct] = ntld4(xr + n0 + wn * 64 + ct * 16 + 4 * g); }
;         __syncthreads();
;     ...
; #pragma unroll
;         for (int tt = 0; tt < 3; ++tt) {
;             const int row = m0 + wm * 48 + tt * 16 + q;
;             const float* xr = row < NTP ? p.x_p + (size_t)row * DM : p.x_s + (size_t)(row - NTP) * DM;
;             float* o = p.out + (size_t)row * DM;
; #pragma unroll
;             for (int ct = 0; ct < 4; ++ct) { const int col = n0 + wn * 64 + ct * 16 + 4 * g; const float4 xv = xres[tt][ct];
;                 const f32x4 w = {xv.x + acc[ct][tt][0], xv.y + acc[ct][tt][1], xv.z + acc[ct][tt][2], xv.w + acc[ct][tt][3]}; __builtin_nontemporal_store(w, (f32x4*)(o + col)); }
;         }
	v_add_f32_e32 v25, v25, v166
	global_store_dword v188, v25, s[52:53] nt
	s_waitcnt vmcnt(63)
	v_add_f32_e32 v9, v9, v167
	global_store_dword v188, v9, s[52:53] offset:128 nt
	v_add_u32_e32 v188, 0x5000, v188
	s_waitcnt vmcnt(63)
	v_add_f32_e32 v26, v26, v168
	global_store_dword v188, v26, s[52:53] nt
	s_waitcnt vmcnt(63)
	v_add_f32_e32 v10, v10, v169
	global_store_dword v188, v10, s[52:53] offset:128 nt
	v_add_u32_e32 v188, 0x1000, v188
	s_waitcnt vmcnt(63)
	v_add_f32_e32 v27, v27, v170
	global_store_dword v188, v27, s[52:53] nt
	s_waitcnt vmcnt(63)
	v_add_f32_e32 v11, v11, v171
	global_store_dword v188, v11, s[52:53] offset:128 nt
	v_add_u32_e32 v188, 0x1000, v188
	s_waitcnt vmcnt(63)
	v_add_f32_e32 v28, v28, v172
	global_store_dword v188, v28, s[52:53] nt
	s_waitcnt vmcnt(63)
	v_add_f32_e32 v12, v12, v173
	global_store_dword v188, v12, s[52:53] offset:128 nt
	v_add_u32_e32 v188, 0x1000, v188
	s_waitcnt vmcnt(63)
	v_add_f32_e32 v29, v29, v174
	global_store_dword v188, v29, s[52:53] nt
	s_waitcnt vmcnt(63)
	v_add_f32_e32 v13, v13, v175
	global_store_dword v188, v13, s[52:53] offset:128 nt
	v_add_u32_e32 v188, 0x5000, v188
	s_waitcnt vmcnt(63)
	v_add_f32_e32 v30, v30, v176
	global_store_dword v188, v30, s[52:53] nt
	s_waitcnt vmcnt(63)
	v_add_f32_e32 v14, v14, v177
	global_store_dword v188, v14, s[52:53] offset:128 nt
	v_add_u32_e32 v188, 0x1000, v188
	s_waitcnt vmcnt(63)
	v_add_f32_e32 v31, v31, v178
	global_store_dword v188, v31, s[52:53] nt
	s_waitcnt vmcnt(63)
	v_add_f32_e32 v15, v15, v179
	global_store_dword v188, v15, s[52:53] offset:128 nt
	v_add_u32_e32 v188, 0x1000, v188
	s_waitcnt vmcnt(63)
	v_add_f32_e32 v32, v32, v180
	global_store_dword v188, v32, s[52:53] nt
	s_waitcnt vmcnt(63)
	v_add_f32_e32 v16, v16, v181
	global_store_dword v188, v16, s[52:53] offset:128 nt
	v_add_u32_e32 v188, 0x1000, v188
	s_waitcnt vmcnt(63)
	v_add_f32_e32 v33, v33, v182
	global_store_dword v188, v33, s[52:53] nt
	s_waitcnt vmcnt(63)
	v_add_f32_e32 v17, v17, v183
	global_store_dword v188, v17, s[52:53] offset:128 nt
	v_readlane_b32 s95, v236, 8
	s_cmpk_lt_i32 s33, 0x400
	s_mov_b32 s0, s88
	s_mov_b32 s82, s86
	s_cbranch_scc1 .Lo_tile
	v_readlane_b32 s2, v236, 3
	s_nop 3
	s_cmp_gt_u32 s2, 0x7f
	s_cbranch_scc1 .LBB0_578
	s_and_b32 s3, s2, 7
	s_lshr_b32 s2, s2, 3
	s_lshl4_add_u32 s2, s3, s2
	s_lshr_b32 s4, s2, 4
	s_lshl_b32 s4, s4, 6
	s_add_i32 s4, s4, 0x4000
	s_and_b32 s5, s2, 15
	s_lshl_b32 s5, s5, 6
	v_readfirstlane_b32 s6, v0
	s_lshr_b32 s6, s6, 6
	s_and_b32 s7, s6, 1
	s_lshr_b32 s8, s6, 1
	s_lshl_b32 s1, s6, 10
	s_lshl_b32 s9, s7, 5
	s_add_i32 s9, s9, s4
	s_lshl_b32 s20, s8, 5
	s_add_i32 s20, s20, s5
	v_and_b32_e32 v24, 31, v0
	v_bfe_u32 v21, v0, 5, 1
	v_add_u32_e32 v23, s20, v24
	v_lshlrev_b32_e32 v34, 14, v21
	v_lshl_add_u32 v34, v23, 2, v34
	s_lshl_b32 s21, s9, 12
	s_sub_i32 s22, s9, 0x4000
	s_lshl_b32 s22, s22, 12
	v_add_u32_e32 v35, s21, v34
	v_add_u32_e32 v34, s22, v34
	global_load_dword v40, v34, s[58:59] nt
	v_add_u32_e32 v34, 0x1000, v34
	global_load_dword v41, v34, s[58:59] nt
	v_add_u32_e32 v34, 0x1000, v34
	global_load_dword v42, v34, s[58:59] nt
	v_add_u32_e32 v34, 0x1000, v34
	global_load_dword v43, v34, s[58:59] nt
	v_add_u32_e32 v34, 0x5000, v34
	global_load_dword v44, v34, s[58:59] nt
	v_add_u32_e32 v34, 0x1000, v34
	global_load_dword v45, v34, s[58:59] nt
	v_add_u32_e32 v34, 0x1000, v34
	global_load_dword v46, v34, s[58:59] nt
	v_add_u32_e32 v34, 0x1000, v34
	global_load_dword v47, v34, s[58:59] nt
	v_add_u32_e32 v34, 0x5000, v34
	global_load_dword v48, v34, s[58:59] nt
	v_add_u32_e32 v34, 0x1000, v34
	global_load_dword v49, v34, s[58:59] nt
	v_add_u32_e32 v34, 0x1000, v34
	global_load_dword v50, v34, s[58:59] nt
	v_add_u32_e32 v34, 0x1000, v34
	global_load_dword v51, v34, s[58:59] nt
	v_add_u32_e32 v34, 0x5000, v34
	global_load_dword v52, v34, s[58:59] nt
	v_add_u32_e32 v34, 0x1000, v34
	global_load_dword v53, v34, s[58:59] nt
	v_add_u32_e32 v34, 0x1000, v34
	global_load_dword v54, v34, s[58:59] nt
	v_add_u32_e32 v34, 0x1000, v34
	global_load_dword v55, v34, s[58:59] nt
	v_bfe_u32 v2, v0, 3, 3
	v_lshl_or_b32 v2, s6, 3, v2
	v_lshrrev_b32_e32 v3, 1, v2
	v_xor_b32_e32 v3, v3, v0
	v_lshlrev_b32_e32 v3, 4, v3
	v_and_b32_e32 v3, 0x70, v3
	v_lshl_or_b32 v6, v2, 11, v3
	v_mov_b32_e32 v7, 0
	s_lshl_b32 s9, s4, 11
	s_add_u32 s10, s54, s9
	s_addc_u32 s11, s55, 0
	s_lshl_b32 s9, s5, 11
	s_add_u32 s12, s54, 0x2940000
	s_addc_u32 s13, s55, 0
	s_add_u32 s12, s12, s9
	s_addc_u32 s13, s13, 0
	s_mov_b64 s[14:15], 0x10000
	s_mov_b64 s[16:17], 0x80
	v_lshl_add_u64 v[10:11], s[10:11], 0, v[6:7]
	v_lshl_add_u64 v[14:15], s[12:13], 0, v[6:7]
	v_lshl_add_u64 v[12:13], v[10:11], 0, s[14:15]
	v_lshl_add_u64 v[16:17], v[14:15], 0, s[14:15]
	v_bfe_u32 v20, v0, 1, 3
	v_xor_b32_e32 v22, v21, v20
	v_lshlrev_b32_e32 v24, 7, v24
	s_lshl_b32 s18, s7, 12
	s_lshl_b32 s19, s8, 12
	s_add_i32 s19, s19, 0x2000
	v_lshl_add_u32 v23, v22, 4, v24
	v_add_u32_e32 v26, s18, v23
	v_add_u32_e32 v30, s19, v23
	v_xor_b32_e32 v23, 2, v22
	v_lshl_add_u32 v23, v23, 4, v24
	v_add_u32_e32 v27, s18, v23
	v_add_u32_e32 v31, s19, v23
	v_xor_b32_e32 v23, 4, v22
	v_lshl_add_u32 v23, v23, 4, v24
	v_add_u32_e32 v28, s18, v23
	v_add_u32_e32 v32, s19, v23
	v_xor_b32_e32 v23, 6, v22
	v_lshl_add_u32 v23, v23, 4, v24
	v_add_u32_e32 v29, s18, v23
	v_add_u32_e32 v33, s19, v23
	s_add_i32 m0, s1, 0x0
	s_nop 0
	global_load_lds_dwordx4 v[10:11], off sc1
	s_add_i32 m0, s1, 0x1000
	v_lshl_add_u64 v[10:11], v[10:11], 0, s[16:17]
	global_load_lds_dwordx4 v[12:13], off sc1
	s_add_i32 m0, s1, 0x2000
	v_lshl_add_u64 v[12:13], v[12:13], 0, s[16:17]
	global_load_lds_dwordx4 v[14:15], off
	s_add_i32 m0, s1, 0x3000
	v_lshl_add_u64 v[14:15], v[14:15], 0, s[16:17]
	global_load_lds_dwordx4 v[16:17], off
	v_lshl_add_u64 v[16:17], v[16:17], 0, s[16:17]
	s_add_i32 m0, s1, 0x4000
	s_nop 0
	global_load_lds_dwordx4 v[10:11], off sc1
	s_add_i32 m0, s1, 0x5000
	v_lshl_add_u64 v[10:11], v[10:11], 0, s[16:17]
	global_load_lds_dwordx4 v[12:13], off sc1
	s_add_i32 m0, s1, 0x6000
	v_lshl_add_u64 v[12:13], v[12:13], 0, s[16:17]
	global_load_lds_dwordx4 v[14:15], off
	s_add_i32 m0, s1, 0x7000
	v_lshl_add_u64 v[14:15], v[14:15], 0, s[16:17]
	global_load_lds_dwordx4 v[16:17], off
	v_lshl_add_u64 v[16:17], v[16:17], 0, s[16:17]
	s_add_i32 m0, s1, 0x8000
	s_nop 0
	global_load_lds_dwordx4 v[10:11], off sc1
	s_add_i32 m0, s1, 0x9000
	v_lshl_add_u64 v[10:11], v[10:11], 0, s[16:17]
	global_load_lds_dwordx4 v[12:13], off sc1
	s_add_i32 m0, s1, 0xa000
	v_lshl_add_u64 v[12:13], v[12:13], 0, s[16:17]
	global_load_lds_dwordx4 v[14:15], off
	s_add_i32 m0, s1, 0xb000
	v_lshl_add_u64 v[14:15], v[14:15], 0, s[16:17]
	global_load_lds_dwordx4 v[16:17], off
	v_lshl_add_u64 v[16:17], v[16:17], 0, s[16:17]
	s_waitcnt vmcnt(8)
	s_barrier
; DI void gemm_out(const Params& p, char* lds) {
;     ...
;         for (int kt = 0; kt < 16; ++kt) {
;             if (kt + 1 < 16) OSTAGE((kt + 1) & 1, kt + 1);
;             const char* sb = lds + (kt & 1) * 28672; const char* sa = sb + 16384;
; #pragma unroll
;             for (int ks = 0; ks < 2; ++ks) {
;                 bf16x8 fw[4], fx[3];
; #pragma unroll
;                 for (int ct = 0; ct < 4; ++ct) fw[ct] = *(const bf16x8*)(sb + swz(wn * 64 + ct * 16 + q, 4 * ks + g));
; #pragma unroll
;                 for (int tt = 0; tt < 3; ++tt) fx[tt] = *(const bf16x8*)(sa + swz(wm * 48 + tt * 16 + q, 4 * ks + g));
; #pragma unroll
;                 for (int ct = 0; ct < 4; ++ct)
; #pragma unroll
;                     for (int tt = 0; tt < 3; ++tt) acc[ct][tt] = __builtin_amdgcn_mfma_f32_16x16x32_bf16(fw[ct], fx[tt], acc[ct][tt], 0, 0, 0);
;             }
;             __syncthreads();
;         }
	s_add_i32 m0, s1, 0xc000
	s_nop 0
	global_load_lds_dwordx4 v[10:11], off sc1
	s_add_i32 m0, s1, 0xd000
	v_lshl_add_u64 v[10:11], v[10:11], 0, s[16:17]
	global_load_lds_dwordx4 v[12:13], off sc1
	s_add_i32 m0, s1, 0xe000
	v_lshl_add_u64 v[12:13], v[12:13], 0, s[16:17]
	global_load_lds_dwordx4 v[14:15], off
	s_add_i32 m0, s1, 0xf000
	v_lshl_add_u64 v[14:15], v[14:15], 0, s[16:17]
	global_load_lds_dwordx4 v[16:17], off
	v_lshl_add_u64 v[16:17], v[16:17], 0, s[16:17]
	ds_read_b128 v[80:83], v26 offset:0
	ds_read_b128 v[96:99], v30 offset:0
	ds_read_b128 v[84:87], v27 offset:0
	ds_read_b128 v[100:103], v31 offset:0
	ds_read_b128 v[88:91], v28 offset:0
	ds_read_b128 v[104:107], v32 offset:0
	ds_read_b128 v[92:95], v29 offset:0
	ds_read_b128 v[108:111], v33 offset:0
	s_waitcnt lgkmcnt(6)
	v_mfma_f32_32x32x16_bf16 v[64:79], v[80:83], v[96:99], 0
	s_waitcnt lgkmcnt(4)
	v_mfma_f32_32x32x16_bf16 v[64:79], v[84:87], v[100:103], v[64:79]
	s_waitcnt lgkmcnt(2)
	v_mfma_f32_32x32x16_bf16 v[64:79], v[88:91], v[104:107], v[64:79]
	s_waitcnt lgkmcnt(0)
	v_mfma_f32_32x32x16_bf16 v[64:79], v[92:95], v[108:111], v[64:79]
	s_waitcnt vmcnt(8)
	s_barrier
	s_add_i32 m0, s1, 0x0
	s_nop 0
	global_load_lds_dwordx4 v[10:11], off sc1
	s_add_i32 m0, s1, 0x1000
	v_lshl_add_u64 v[10:11], v[10:11], 0, s[16:17]
	global_load_lds_dwordx4 v[12:13], off sc1
	s_add_i32 m0, s1, 0x2000
	v_lshl_add_u64 v[12:13], v[12:13], 0, s[16:17]
	global_load_lds_dwordx4 v[14:15], off
	s_add_i32 m0, s1, 0x3000
	v_lshl_add_u64 v[14:15], v[14:15], 0, s[16:17]
	global_load_lds_dwordx4 v[16:17], off
	v_lshl_add_u64 v[16:17], v[16:17], 0, s[16:17]
	ds_read_b128 v[80:83], v26 offset:16384
	ds_read_b128 v[96:99], v30 offset:16384
	ds_read_b128 v[84:87], v27 offset:16384
	ds_read_b128 v[100:103], v31 offset:16384
	ds_read_b128 v[88:91], v28 offset:16384
	ds_read_b128 v[104:107], v32 offset:16384
	ds_read_b128 v[92:95], v29 offset:16384
	ds_read_b128 v[108:111], v33 offset:16384
	s_waitcnt lgkmcnt(6)
	v_mfma_f32_32x32x16_bf16 v[64:79], v[80:83], v[96:99], v[64:79]
	s_waitcnt lgkmcnt(4)
	v_mfma_f32_32x32x16_bf16 v[64:79], v[84:87], v[100:103], v[64:79]
	s_waitcnt lgkmcnt(2)
	v_mfma_f32_32x32x16_bf16 v[64:79], v[88:91], v[104:107], v[64:79]
	s_waitcnt lgkmcnt(0)
	v_mfma_f32_32x32x16_bf16 v[64:79], v[92:95], v[108:111], v[64:79]
	s_waitcnt vmcnt(8)
	s_barrier
	s_add_i32 m0, s1, 0x4000
	s_nop 0
	global_load_lds_dwordx4 v[10:11], off sc1
	s_add_i32 m0, s1, 0x5000
	v_lshl_add_u64 v[10:11], v[10:11], 0, s[16:17]
	global_load_lds_dwordx4 v[12:13], off sc1
	s_add_i32 m0, s1, 0x6000
	v_lshl_add_u64 v[12:13], v[12:13], 0, s[16:17]
	global_load_lds_dwordx4 v[14:15], off
	s_add_i32 m0, s1, 0x7000
	v_lshl_add_u64 v[14:15], v[14:15], 0, s[16:17]
	global_load_lds_dwordx4 v[16:17], off
	v_lshl_add_u64 v[16:17], v[16:17], 0, s[16:17]
	ds_read_b128 v[80:83], v26 offset:32768
	ds_read_b128 v[96:99], v30 offset:32768
	ds_read_b128 v[84:87], v27 offset:32768
	ds_read_b128 v[100:103], v31 offset:32768
	ds_read_b128 v[88:91], v28 offset:32768
	ds_read_b128 v[104:107], v32 offset:32768
	ds_read_b128 v[92:95], v29 offset:32768
	ds_read_b128 v[108:111], v33 offset:32768
	s_waitcnt lgkmcnt(6)
	v_mfma_f32_32x32x16_bf16 v[64:79], v[80:83], v[96:99], v[64:79]
	s_waitcnt lgkmcnt(4)
	v_mfma_f32_32x32x16_bf16 v[64:79], v[84:87], v[100:103], v[64:79]
	s_waitcnt lgkmcnt(2)
	v_mfma_f32_32x32x16_bf16 v[64:79], v[88:91], v[104:107], v[64:79]
	s_waitcnt lgkmcnt(0)
	v_mfma_f32_32x32x16_bf16 v[64:79], v[92:95], v[108:111], v[64:79]
	s_waitcnt vmcnt(8)
	s_barrier
	s_add_i32 m0, s1, 0x8000
	s_nop 0
	global_load_lds_dwordx4 v[10:11], off sc1
	s_add_i32 m0, s1, 0x9000
	v_lshl_add_u64 v[10:11], v[10:11], 0, s[16:17]
	global_load_lds_dwordx4 v[12:13], off sc1
	s_add_i32 m0, s1, 0xa000
	v_lshl_add_u64 v[12:13], v[12:13], 0, s[16:17]
	global_load_lds_dwordx4 v[14:15], off
	s_add_i32 m0, s1, 0xb000
	v_lshl_add_u64 v[14:15], v[14:15], 0, s[16:17]
	global_load_lds_dwordx4 v[16:17], off
	v_lshl_add_u64 v[16:17], v[16:17], 0, s[16:17]
	ds_read_b128 v[80:83], v26 offset:49152
	ds_read_b128 v[96:99], v30 offset:49152
	ds_read_b128 v[84:87], v27 offset:49152
	ds_read_b128 v[100:103], v31 offset:49152
	ds_read_b128 v[88:91], v28 offset:49152
	ds_read_b128 v[104:107], v32 offset:49152
	ds_read_b128 v[92:95], v29 offset:49152
	ds_read_b128 v[108:111], v33 offset:49152
	s_waitcnt lgkmcnt(6)
	v_mfma_f32_32x32x16_bf16 v[64:79], v[80:83], v[96:99], v[64:79]
	s_waitcnt lgkmcnt(4)
	v_mfma_f32_32x32x16_bf16 v[64:79], v[84:87], v[100:103], v[64:79]
	s_waitcnt lgkmcnt(2)
	v_mfma_f32_32x32x16_bf16 v[64:79], v[88:91], v[104:107], v[64:79]
	s_waitcnt lgkmcnt(0)
	v_mfma_f32_32x32x16_bf16 v[64:79], v[92:95], v[108:111], v[64:79]
	s_waitcnt vmcnt(8)
	s_barrier
	s_add_i32 m0, s1, 0xc000
	s_nop 0
	global_load_lds_dwordx4 v[10:11], off sc1
	s_add_i32 m0, s1, 0xd000
	v_lshl_add_u64 v[10:11], v[10:11], 0, s[16:17]
	global_load_lds_dwordx4 v[12:13], off sc1
	s_add_i32 m0, s1, 0xe000
	v_lshl_add_u64 v[12:13], v[12:13], 0, s[16:17]
	global_load_lds_dwordx4 v[14:15], off
	s_add_i32 m0, s1, 0xf000
	v_lshl_add_u64 v[14:15], v[14:15], 0, s[16:17]
	global_load_lds_dwordx4 v[16:17], off
	v_lshl_add_u64 v[16:17], v[16:17], 0, s[16:17]
	ds_read_b128 v[80:83], v26 offset:0
	ds_read_b128 v[96:99], v30 offset:0
	ds_read_b128 v[84:87], v27 offset:0
	ds_read_b128 v[100:103], v31 offset:0
	ds_read_b128 v[88:91], v28 offset:0
	ds_read_b128 v[104:107], v32 offset:0
	ds_read_b128 v[92:95], v29 offset:0
	ds_read_b128 v[108:111], v33 offset:0
	s_waitcnt lgkmcnt(6)
	v_mfma_f32_32x32x16_bf16 v[64:79], v[80:83], v[96:99], v[64:79]
	s_waitcnt lgkmcnt(4)
	v_mfma_f32_32x32x16_bf16 v[64:79], v[84:87], v[100:103], v[64:79]
	s_waitcnt lgkmcnt(2)
	v_mfma_f32_32x32x16_bf16 v[64:79], v[88:91], v[104:107], v[64:79]
	s_waitcnt lgkmcnt(0)
	v_mfma_f32_32x32x16_bf16 v[64:79], v[92:95], v[108:111], v[64:79]
	s_waitcnt vmcnt(8)
	s_barrier
; DI void gemm_out(const Params& p, char* lds) {
;     ...
;         for (int kt = 0; kt < 16; ++kt) {
;             if (kt + 1 < 16) OSTAGE((kt + 1) & 1, kt + 1);
;             const char* sb = lds + (kt & 1) * 28672; const char* sa = sb + 16384;
; #pragma unroll
;             for (int ks = 0; ks < 2; ++ks) {
;                 bf16x8 fw[4], fx[3];
; #pragma unroll
;                 for (int ct = 0; ct < 4; ++ct) fw[ct] = *(const bf16x8*)(sb + swz(wn * 64 + ct * 16 + q, 4 * ks + g));
; #pragma unroll
;                 for (int tt = 0; tt < 3; ++tt) fx[tt] = *(const bf16x8*)(sa + swz(wm * 48 + tt * 16 + q, 4 * ks + g));
; #pragma unroll
;                 for (int ct = 0; ct < 4; ++ct)
; #pragma unroll
;                     for (int tt = 0; tt < 3; ++tt) acc[ct][tt] = __builtin_amdgcn_mfma_f32_16x16x32_bf16(fw[ct], fx[tt], acc[ct][tt], 0, 0, 0);
;             }
;             __syncthreads();
;         }
	s_add_i32 m0, s1, 0x0
	s_nop 0
	global_load_lds_dwordx4 v[10:11], off sc1
	s_add_i32 m0, s1, 0x1000
	v_lshl_add_u64 v[10:11], v[10:11], 0, s[16:17]
	global_load_lds_dwordx4 v[12:13], off sc1
	s_add_i32 m0, s1, 0x2000
	v_lshl_add_u64 v[12:13], v[12:13], 0, s[16:17]
	global_load_lds_dwordx4 v[14:15], off
	s_add_i32 m0, s1, 0x3000
	v_lshl_add_u64 v[14:15], v[14:15], 0, s[16:17]
	global_load_lds_dwordx4 v[16:17], off
	v_lshl_add_u64 v[16:17], v[16:17], 0, s[16:17]
	ds_read_b128 v[80:83], v26 offset:16384
	ds_read_b128 v[96:99], v30 offset:16384
	ds_read_b128 v[84:87], v27 offset:16384
	ds_read_b128 v[100:103], v31 offset:16384
	ds_read_b128 v[88:91], v28 offset:16384
	ds_read_b128 v[104:107], v32 offset:16384
	ds_read_b128 v[92:95], v29 offset:16384
	ds_read_b128 v[108:111], v33 offset:16384
	s_waitcnt lgkmcnt(6)
	v_mfma_f32_32x32x16_bf16 v[64:79], v[80:83], v[96:99], v[64:79]
	s_waitcnt lgkmcnt(4)
	v_mfma_f32_32x32x16_bf16 v[64:79], v[84:87], v[100:103], v[64:79]
	s_waitcnt lgkmcnt(2)
	v_mfma_f32_32x32x16_bf16 v[64:79], v[88:91], v[104:107], v[64:79]
	s_waitcnt lgkmcnt(0)
	v_mfma_f32_32x32x16_bf16 v[64:79], v[92:95], v[108:111], v[64:79]
	s_waitcnt vmcnt(8)
	s_barrier
	s_add_i32 m0, s1, 0x4000
	s_nop 0
	global_load_lds_dwordx4 v[10:11], off sc1
	s_add_i32 m0, s1, 0x5000
	v_lshl_add_u64 v[10:11], v[10:11], 0, s[16:17]
	global_load_lds_dwordx4 v[12:13], off sc1
	s_add_i32 m0, s1, 0x6000
	v_lshl_add_u64 v[12:13], v[12:13], 0, s[16:17]
	global_load_lds_dwordx4 v[14:15], off
	s_add_i32 m0, s1, 0x7000
	v_lshl_add_u64 v[14:15], v[14:15], 0, s[16:17]
	global_load_lds_dwordx4 v[16:17], off
	v_lshl_add_u64 v[16:17], v[16:17], 0, s[16:17]
	ds_read_b128 v[80:83], v26 offset:32768
	ds_read_b128 v[96:99], v30 offset:32768
	ds_read_b128 v[84:87], v27 offset:32768
	ds_read_b128 v[100:103], v31 offset:32768
	ds_read_b128 v[88:91], v28 offset:32768
	ds_read_b128 v[104:107], v32 offset:32768
	ds_read_b128 v[92:95], v29 offset:32768
	ds_read_b128 v[108:111], v33 offset:32768
	s_waitcnt lgkmcnt(6)
	v_mfma_f32_32x32x16_bf16 v[64:79], v[80:83], v[96:99], v[64:79]
	s_waitcnt lgkmcnt(4)
	v_mfma_f32_32x32x16_bf16 v[64:79], v[84:87], v[100:103], v[64:79]
	s_waitcnt lgkmcnt(2)
	v_mfma_f32_32x32x16_bf16 v[64:79], v[88:91], v[104:107], v[64:79]
	s_waitcnt lgkmcnt(0)
	v_mfma_f32_32x32x16_bf16 v[64:79], v[92:95], v[108:111], v[64:79]
	s_waitcnt vmcnt(8)
	s_barrier
	s_add_i32 m0, s1, 0x8000
	s_nop 0
	global_load_lds_dwordx4 v[10:11], off sc1
	s_add_i32 m0, s1, 0x9000
	v_lshl_add_u64 v[10:11], v[10:11], 0, s[16:17]
	global_load_lds_dwordx4 v[12:13], off sc1
	s_add_i32 m0, s1, 0xa000
	v_lshl_add_u64 v[12:13], v[12:13], 0, s[16:17]
	global_load_lds_dwordx4 v[14:15], off
	s_add_i32 m0, s1, 0xb000
	v_lshl_add_u64 v[14:15], v[14:15], 0, s[16:17]
	global_load_lds_dwordx4 v[16:17], off
	v_lshl_add_u64 v[16:17], v[16:17], 0, s[16:17]
	ds_read_b128 v[80:83], v26 offset:49152
	ds_read_b128 v[96:99], v30 offset:49152
	ds_read_b128 v[84:87], v27 offset:49152
	ds_read_b128 v[100:103], v31 offset:49152
	ds_read_b128 v[88:91], v28 offset:49152
	ds_read_b128 v[104:107], v32 offset:49152
	ds_read_b128 v[92:95], v29 offset:49152
	ds_read_b128 v[108:111], v33 offset:49152
	s_waitcnt lgkmcnt(6)
	v_mfma_f32_32x32x16_bf16 v[64:79], v[80:83], v[96:99], v[64:79]
	s_waitcnt lgkmcnt(4)
	v_mfma_f32_32x32x16_bf16 v[64:79], v[84:87], v[100:103], v[64:79]
	s_waitcnt lgkmcnt(2)
	v_mfma_f32_32x32x16_bf16 v[64:79], v[88:91], v[104:107], v[64:79]
	s_waitcnt lgkmcnt(0)
	v_mfma_f32_32x32x16_bf16 v[64:79], v[92:95], v[108:111], v[64:79]
	s_waitcnt vmcnt(8)
	s_barrier
	s_add_i32 m0, s1, 0xc000
	s_nop 0
	global_load_lds_dwordx4 v[10:11], off sc1
	s_add_i32 m0, s1, 0xd000
	v_lshl_add_u64 v[10:11], v[10:11], 0, s[16:17]
	global_load_lds_dwordx4 v[12:13], off sc1
	s_add_i32 m0, s1, 0xe000
	v_lshl_add_u64 v[12:13], v[12:13], 0, s[16:17]
	global_load_lds_dwordx4 v[14:15], off
	s_add_i32 m0, s1, 0xf000
	v_lshl_add_u64 v[14:15], v[14:15], 0, s[16:17]
	global_load_lds_dwordx4 v[16:17], off
	v_lshl_add_u64 v[16:17], v[16:17], 0, s[16:17]
	ds_read_b128 v[80:83], v26 offset:0
	ds_read_b128 v[96:99], v30 offset:0
	ds_read_b128 v[84:87], v27 offset:0
	ds_read_b128 v[100:103], v31 offset:0
	ds_read_b128 v[88:91], v28 offset:0
	ds_read_b128 v[104:107], v32 offset:0
	ds_read_b128 v[92:95], v29 offset:0
	ds_read_b128 v[108:111], v33 offset:0
	s_waitcnt lgkmcnt(6)
	v_mfma_f32_32x32x16_bf16 v[64:79], v[80:83], v[96:99], v[64:79]
	s_waitcnt lgkmcnt(4)
	v_mfma_f32_32x32x16_bf16 v[64:79], v[84:87], v[100:103], v[64:79]
	s_waitcnt lgkmcnt(2)
	v_mfma_f32_32x32x16_bf16 v[64:79], v[88:91], v[104:107], v[64:79]
	s_waitcnt lgkmcnt(0)
	v_mfma_f32_32x32x16_bf16 v[64:79], v[92:95], v[108:111], v[64:79]
	s_waitcnt vmcnt(8)
	s_barrier
	s_add_i32 m0, s1, 0x0
	s_nop 0
	global_load_lds_dwordx4 v[10:11], off sc1
	s_add_i32 m0, s1, 0x1000
	v_lshl_add_u64 v[10:11], v[10:11], 0, s[16:17]
	global_load_lds_dwordx4 v[12:13], off sc1
	s_add_i32 m0, s1, 0x2000
	v_lshl_add_u64 v[12:13], v[12:13], 0, s[16:17]
	global_load_lds_dwordx4 v[14:15], off
	s_add_i32 m0, s1, 0x3000
	v_lshl_add_u64 v[14:15], v[14:15], 0, s[16:17]
	global_load_lds_dwordx4 v[16:17], off
	v_lshl_add_u64 v[16:17], v[16:17], 0, s[16:17]
	ds_read_b128 v[80:83], v26 offset:16384
	ds_read_b128 v[96:99], v30 offset:16384
	ds_read_b128 v[84:87], v27 offset:16384
	ds_read_b128 v[100:103], v31 offset:16384
	ds_read_b128 v[88:91], v28 offset:16384
	ds_read_b128 v[104:107], v32 offset:16384
	ds_read_b128 v[92:95], v29 offset:16384
	ds_read_b128 v[108:111], v33 offset:16384
	s_waitcnt lgkmcnt(6)
	v_mfma_f32_32x32x16_bf16 v[64:79], v[80:83], v[96:99], v[64:79]
	s_waitcnt lgkmcnt(4)
	v_mfma_f32_32x32x16_bf16 v[64:79], v[84:87], v[100:103], v[64:79]
	s_waitcnt lgkmcnt(2)
	v_mfma_f32_32x32x16_bf16 v[64:79], v[88:91], v[104:107], v[64:79]
	s_waitcnt lgkmcnt(0)
	v_mfma_f32_32x32x16_bf16 v[64:79], v[92:95], v[108:111], v[64:79]
	s_waitcnt vmcnt(8)
	s_barrier
; DI void gemm_out(const Params& p, char* lds) {
;     ...
;         for (int kt = 0; kt < 16; ++kt) {
;             if (kt + 1 < 16) OSTAGE((kt + 1) & 1, kt + 1);
;             const char* sb = lds + (kt & 1) * 28672; const char* sa = sb + 16384;
; #pragma unroll
;             for (int ks = 0; ks < 2; ++ks) {
;                 bf16x8 fw[4], fx[3];
; #pragma unroll
;                 for (int ct = 0; ct < 4; ++ct) fw[ct] = *(const bf16x8*)(sb + swz(wn * 64 + ct * 16 + q, 4 * ks + g));
; #pragma unroll
;                 for (int tt = 0; tt < 3; ++tt) fx[tt] = *(const bf16x8*)(sa + swz(wm * 48 + tt * 16 + q, 4 * ks + g));
; #pragma unroll
;                 for (int ct = 0; ct < 4; ++ct)
; #pragma unroll
;                     for (int tt = 0; tt < 3; ++tt) acc[ct][tt] = __builtin_amdgcn_mfma_f32_16x16x32_bf16(fw[ct], fx[tt], acc[ct][tt], 0, 0, 0);
;             }
;             __syncthreads();
;         }
	s_add_i32 m0, s1, 0x4000
	s_nop 0
	global_load_lds_dwordx4 v[10:11], off sc1
	s_add_i32 m0, s1, 0x5000
	v_lshl_add_u64 v[10:11], v[10:11], 0, s[16:17]
	global_load_lds_dwordx4 v[12:13], off sc1
	s_add_i32 m0, s1, 0x6000
	v_lshl_add_u64 v[12:13], v[12:13], 0, s[16:17]
	global_load_lds_dwordx4 v[14:15], off
	s_add_i32 m0, s1, 0x7000
	v_lshl_add_u64 v[14:15], v[14:15], 0, s[16:17]
	global_load_lds_dwordx4 v[16:17], off
	v_lshl_add_u64 v[16:17], v[16:17], 0, s[16:17]
	ds_read_b128 v[80:83], v26 offset:32768
	ds_read_b128 v[96:99], v30 offset:32768
	ds_read_b128 v[84:87], v27 offset:32768
	ds_read_b128 v[100:103], v31 offset:32768
	ds_read_b128 v[88:91], v28 offset:32768
	ds_read_b128 v[104:107], v32 offset:32768
	ds_read_b128 v[92:95], v29 offset:32768
	ds_read_b128 v[108:111], v33 offset:32768
	s_waitcnt lgkmcnt(6)
	v_mfma_f32_32x32x16_bf16 v[64:79], v[80:83], v[96:99], v[64:79]
	s_waitcnt lgkmcnt(4)
	v_mfma_f32_32x32x16_bf16 v[64:79], v[84:87], v[100:103], v[64:79]
	s_waitcnt lgkmcnt(2)
	v_mfma_f32_32x32x16_bf16 v[64:79], v[88:91], v[104:107], v[64:79]
	s_waitcnt lgkmcnt(0)
	v_mfma_f32_32x32x16_bf16 v[64:79], v[92:95], v[108:111], v[64:79]
	s_waitcnt vmcnt(8)
	s_barrier
	s_add_i32 m0, s1, 0x8000
	s_nop 0
	global_load_lds_dwordx4 v[10:11], off sc1
	s_add_i32 m0, s1, 0x9000
	v_lshl_add_u64 v[10:11], v[10:11], 0, s[16:17]
	global_load_lds_dwordx4 v[12:13], off sc1
	s_add_i32 m0, s1, 0xa000
	v_lshl_add_u64 v[12:13], v[12:13], 0, s[16:17]
	global_load_lds_dwordx4 v[14:15], off
	s_add_i32 m0, s1, 0xb000
	v_lshl_add_u64 v[14:15], v[14:15], 0, s[16:17]
	global_load_lds_dwordx4 v[16:17], off
	v_lshl_add_u64 v[16:17], v[16:17], 0, s[16:17]
	ds_read_b128 v[80:83], v26 offset:49152
	ds_read_b128 v[96:99], v30 offset:49152
	ds_read_b128 v[84:87], v27 offset:49152
	ds_read_b128 v[100:103], v31 offset:49152
	ds_read_b128 v[88:91], v28 offset:49152
	ds_read_b128 v[104:107], v32 offset:49152
	ds_read_b128 v[92:95], v29 offset:49152
	ds_read_b128 v[108:111], v33 offset:49152
	s_waitcnt lgkmcnt(6)
	v_mfma_f32_32x32x16_bf16 v[64:79], v[80:83], v[96:99], v[64:79]
	s_waitcnt lgkmcnt(4)
	v_mfma_f32_32x32x16_bf16 v[64:79], v[84:87], v[100:103], v[64:79]
	s_waitcnt lgkmcnt(2)
	v_mfma_f32_32x32x16_bf16 v[64:79], v[88:91], v[104:107], v[64:79]
	s_waitcnt lgkmcnt(0)
	v_mfma_f32_32x32x16_bf16 v[64:79], v[92:95], v[108:111], v[64:79]
	s_waitcnt vmcnt(8)
	s_barrier
	s_add_i32 m0, s1, 0xc000
	s_nop 0
	global_load_lds_dwordx4 v[10:11], off sc1
	s_add_i32 m0, s1, 0xd000
	v_lshl_add_u64 v[10:11], v[10:11], 0, s[16:17]
	global_load_lds_dwordx4 v[12:13], off sc1
	s_add_i32 m0, s1, 0xe000
	v_lshl_add_u64 v[12:13], v[12:13], 0, s[16:17]
	global_load_lds_dwordx4 v[14:15], off
	s_add_i32 m0, s1, 0xf000
	v_lshl_add_u64 v[14:15], v[14:15], 0, s[16:17]
	global_load_lds_dwordx4 v[16:17], off
	v_lshl_add_u64 v[16:17], v[16:17], 0, s[16:17]
	ds_read_b128 v[80:83], v26 offset:0
	ds_read_b128 v[96:99], v30 offset:0
	ds_read_b128 v[84:87], v27 offset:0
	ds_read_b128 v[100:103], v31 offset:0
	ds_read_b128 v[88:91], v28 offset:0
	ds_read_b128 v[104:107], v32 offset:0
	ds_read_b128 v[92:95], v29 offset:0
	ds_read_b128 v[108:111], v33 offset:0
	s_waitcnt lgkmcnt(6)
	v_mfma_f32_32x32x16_bf16 v[64:79], v[80:83], v[96:99], v[64:79]
	s_waitcnt lgkmcnt(4)
	v_mfma_f32_32x32x16_bf16 v[64:79], v[84:87], v[100:103], v[64:79]
	s_waitcnt lgkmcnt(2)
	v_mfma_f32_32x32x16_bf16 v[64:79], v[88:91], v[104:107], v[64:79]
	s_waitcnt lgkmcnt(0)
	v_mfma_f32_32x32x16_bf16 v[64:79], v[92:95], v[108:111], v[64:79]
	s_waitcnt vmcnt(8)
	s_barrier
; DI void gemm_out(const Params& p, char* lds) {
;     ...
;         for (int kt = 0; kt < 16; ++kt) {
;             if (kt + 1 < 16) OSTAGE((kt + 1) & 1, kt + 1);
;             const char* sb = lds + (kt & 1) * 28672; const char* sa = sb + 16384;
; #pragma unroll
;             for (int ks = 0; ks < 2; ++ks) {
;                 bf16x8 fw[4], fx[3];
; #pragma unroll
;                 for (int ct = 0; ct < 4; ++ct) fw[ct] = *(const bf16x8*)(sb + swz(wn * 64 + ct * 16 + q, 4 * ks + g));
; #pragma unroll
;                 for (int tt = 0; tt < 3; ++tt) fx[tt] = *(const bf16x8*)(sa + swz(wm * 48 + tt * 16 + q, 4 * ks + g));
; #pragma unroll
;                 for (int ct = 0; ct < 4; ++ct)
; #pragma unroll
;                     for (int tt = 0; tt < 3; ++tt) acc[ct][tt] = __builtin_amdgcn_mfma_f32_16x16x32_bf16(fw[ct], fx[tt], acc[ct][tt], 0, 0, 0);
;             }
;             __syncthreads();
;         }
;     ...
; #pragma unroll
;         for (int tt = 0; tt < 3; ++tt) {
;             const int row = m0 + wm * 48 + tt * 16 + q;
;             const float* xr = row < NTP ? p.x_p + (size_t)row * DM : p.x_s + (size_t)(row - NTP) * DM;
;             float* o = p.out + (size_t)row * DM;
; #pragma unroll
;             for (int ct = 0; ct < 4; ++ct) { const int col = n0 + wn * 64 + ct * 16 + 4 * g; const float4 xv = xres[tt][ct];
;                 const f32x4 w = {xv.x + acc[ct][tt][0], xv.y + acc[ct][tt][1], xv.z + acc[ct][tt][2], xv.w + acc[ct][tt][3]}; __builtin_nontemporal_store(w, (f32x4*)(o + col)); }
;         }
	ds_read_b128 v[80:83], v26 offset:16384
	ds_read_b128 v[96:99], v30 offset:16384
	ds_read_b128 v[84:87], v27 offset:16384
	ds_read_b128 v[100:103], v31 offset:16384
	ds_read_b128 v[88:91], v28 offset:16384
	ds_read_b128 v[104:107], v32 offset:16384
	ds_read_b128 v[92:95], v29 offset:16384
	ds_read_b128 v[108:111], v33 offset:16384
	s_waitcnt lgkmcnt(6)
	v_mfma_f32_32x32x16_bf16 v[64:79], v[80:83], v[96:99], v[64:79]
	s_waitcnt lgkmcnt(4)
	v_mfma_f32_32x32x16_bf16 v[64:79], v[84:87], v[100:103], v[64:79]
	s_waitcnt lgkmcnt(2)
	v_mfma_f32_32x32x16_bf16 v[64:79], v[88:91], v[104:107], v[64:79]
	s_waitcnt lgkmcnt(0)
	v_mfma_f32_32x32x16_bf16 v[64:79], v[92:95], v[108:111], v[64:79]
	s_waitcnt vmcnt(4)
	s_barrier
	ds_read_b128 v[80:83], v26 offset:32768
	ds_read_b128 v[96:99], v30 offset:32768
	ds_read_b128 v[84:87], v27 offset:32768
	ds_read_b128 v[100:103], v31 offset:32768
	ds_read_b128 v[88:91], v28 offset:32768
	ds_read_b128 v[104:107], v32 offset:32768
	ds_read_b128 v[92:95], v29 offset:32768
	ds_read_b128 v[108:111], v33 offset:32768
	s_waitcnt lgkmcnt(6)
	v_mfma_f32_32x32x16_bf16 v[64:79], v[80:83], v[96:99], v[64:79]
	s_waitcnt lgkmcnt(4)
	v_mfma_f32_32x32x16_bf16 v[64:79], v[84:87], v[100:103], v[64:79]
	s_waitcnt lgkmcnt(2)
	v_mfma_f32_32x32x16_bf16 v[64:79], v[88:91], v[104:107], v[64:79]
	s_waitcnt lgkmcnt(0)
	v_mfma_f32_32x32x16_bf16 v[64:79], v[92:95], v[108:111], v[64:79]
	s_waitcnt vmcnt(0)
	s_barrier
	ds_read_b128 v[80:83], v26 offset:49152
	ds_read_b128 v[96:99], v30 offset:49152
	ds_read_b128 v[84:87], v27 offset:49152
	ds_read_b128 v[100:103], v31 offset:49152
	ds_read_b128 v[88:91], v28 offset:49152
	ds_read_b128 v[104:107], v32 offset:49152
	ds_read_b128 v[92:95], v29 offset:49152
	ds_read_b128 v[108:111], v33 offset:49152
	s_waitcnt lgkmcnt(6)
	v_mfma_f32_32x32x16_bf16 v[64:79], v[80:83], v[96:99], v[64:79]
	s_waitcnt lgkmcnt(4)
	v_mfma_f32_32x32x16_bf16 v[64:79], v[84:87], v[100:103], v[64:79]
	s_waitcnt lgkmcnt(2)
	v_mfma_f32_32x32x16_bf16 v[64:79], v[88:91], v[104:107], v[64:79]
	s_waitcnt lgkmcnt(0)
	v_mfma_f32_32x32x16_bf16 v[64:79], v[92:95], v[108:111], v[64:79]
	s_nop 15
	s_nop 7
	v_add_f32_e32 v64, v64, v40
	global_store_dword v35, v64, s[52:53] nt
	v_add_u32_e32 v35, 0x1000, v35
	v_add_f32_e32 v65, v65, v41
	global_store_dword v35, v65, s[52:53] nt
	v_add_u32_e32 v35, 0x1000, v35
	v_add_f32_e32 v66, v66, v42
	global_store_dword v35, v66, s[52:53] nt
	v_add_u32_e32 v35, 0x1000, v35
	v_add_f32_e32 v67, v67, v43
	global_store_dword v35, v67, s[52:53] nt
	v_add_u32_e32 v35, 0x5000, v35
	v_add_f32_e32 v68, v68, v44
	global_store_dword v35, v68, s[52:53] nt
	v_add_u32_e32 v35, 0x1000, v35
	v_add_f32_e32 v69, v69, v45
	global_store_dword v35, v69, s[52:53] nt
	v_add_u32_e32 v35, 0x1000, v35
	v_add_f32_e32 v70, v70, v46
	global_store_dword v35, v70, s[52:53] nt
	v_add_u32_e32 v35, 0x1000, v35
	v_add_f32_e32 v71, v71, v47
	global_store_dword v35, v71, s[52:53] nt
	v_add_u32_e32 v35, 0x5000, v35
	v_add_f32_e32 v72, v72, v48
	global_store_dword v35, v72, s[52:53] nt
	v_add_u32_e32 v35, 0x1000, v35
	v_add_f32_e32 v73, v73, v49
	global_store_dword v35, v73, s[52:53] nt
	v_add_u32_e32 v35, 0x1000, v35
	v_add_f32_e32 v74, v74, v50
	global_store_dword v35, v74, s[52:53] nt
	v_add_u32_e32 v35, 0x1000, v35
	v_add_f32_e32 v75, v75, v51
	global_store_dword v35, v75, s[52:53] nt
	v_add_u32_e32 v35, 0x5000, v35
	v_add_f32_e32 v76, v76, v52
	global_store_dword v35, v76, s[52:53] nt
	v_add_u32_e32 v35, 0x1000, v35
	v_add_f32_e32 v77, v77, v53
	global_store_dword v35, v77, s[52:53] nt
	v_add_u32_e32 v35, 0x1000, v35
	v_add_f32_e32 v78, v78, v54
	global_store_dword v35, v78, s[52:53] nt
	v_add_u32_e32 v35, 0x1000, v35
	v_add_f32_e32 v79, v79, v55
	global_store_dword v35, v79, s[52:53] nt
